# gMLP task loop: V prefetch + LDS skew; winbf inner loop batched LDS reads + packed FMAs; winbf tasks rebalanced to WGs 0-127
# baseline (speedup 1.0000x reference)
; #define LAS __attribute__((address_space(3)))
; __device__ __forceinline__ int tid_l() { int t = threadIdx.x; asm volatile("" : "+v"(t)); return t; }
; __device__ __forceinline__ void winbf_task(LAS unsigned char* lds, const float* w_in_l, bf16_t* dst, int task) {
;     const int tid = tid_l(), g = task & 3, k0 = (task >> 2) * 64;
;     LAS float* Wt = (LAS float*)lds;
;     LAS float* tc = Wt + 64 * 128; LAS float* ts = tc + 128;
;     { const int k = tid >> 3, c16 = (tid & 7) * 16; const float* s = w_in_l + (size_t)(k0 + k) * INW + 1536 + g * 128 + c16;
; __global__ void __launch_bounds__(NTHREADS, 2) mega_fwd(Args a) {
;     ...
;             for (int t = (bx + G - 48) % G; t < 128; t += G) winbf_task(lds, a.in[3] + (size_t)l * 2048 * INW, WINBF, t);
.LBB0_64:
	s_abs_i32 s0, s42
	s_waitcnt vmcnt(0)
	v_cvt_f32_u32_e32 v0, s0
	s_add_i32 s2, s42, s48
	s_sub_i32 s28, s2, 48
	s_sub_i32 s2, 48, s2
	v_rcp_iflag_f32_e32 v0, v0
	s_ashr_i32 s29, s28, 31
	s_max_i32 s2, s28, s2
	s_sub_i32 s28, 0, s0
	v_mul_f32_e32 v0, 0x4f7ffffe, v0
	v_cvt_u32_f32_e32 v0, v0
	s_nop 0
	v_readfirstlane_b32 s31, v0
	s_mul_i32 s28, s28, s31
	s_mul_hi_u32 s28, s31, s28
	s_add_i32 s31, s31, s28
	s_mul_hi_u32 s28, s2, s31
	s_mul_i32 s28, s28, s0
	s_sub_i32 s2, s2, s28
	s_sub_i32 s28, s2, s0
	s_cmp_ge_u32 s2, s0
	s_cselect_b32 s2, s28, s2
	s_sub_i32 s28, s2, s0
	s_cmp_ge_u32 s2, s0
	s_cselect_b32 s0, s28, s2
	s_xor_b32 s0, s0, s29
	s_sub_i32 s0, s0, s29
	s_mov_b32 s0, s48
	s_cmpk_gt_i32 s0, 0x7f
	s_cbranch_scc1 .LBB0_71
	s_mul_i32 s90, s30, 0x580000
	v_readlane_b32 s4, v253, 4
	s_lshl_b64 s[28:29], s[90:91], 2
	v_readlane_b32 s10, v253, 10
	v_readlane_b32 s11, v253, 11
	s_add_u32 s28, s10, s28
	s_addc_u32 s29, s11, s29
	s_add_u32 s34, s44, 0x900000
	s_addc_u32 s35, s45, 0
	v_readlane_b32 s5, v253, 5
	v_readlane_b32 s6, v253, 6
	v_readlane_b32 s7, v253, 7
	v_readlane_b32 s8, v253, 8
	v_readlane_b32 s9, v253, 9
	v_readlane_b32 s12, v253, 12
	v_readlane_b32 s13, v253, 13
	v_readlane_b32 s14, v253, 14
	v_readlane_b32 s15, v253, 15
	v_readlane_b32 s16, v253, 16
	v_readlane_b32 s17, v253, 17
	v_readlane_b32 s18, v253, 18
	v_readlane_b32 s19, v253, 19

; __device__ __forceinline__ void winbf_task(LAS unsigned char* lds, const float* w_in_l, bf16_t* dst, int task) {
;     ...
;     const int cp = tid & 127, kq = tid >> 7;
;     float aC[16], aS[16];
; #pragma unroll
;     for (int kk = 0; kk < 16; ++kk) { aC[kk] = 0.f; aS[kk] = 0.f; }
.LBB0_68:
	s_or_b64 exec, exec, s[38:39]
	v_ashrrev_i32_e32 v65, 7, v64
	v_mov_b32_e32 v34, 0
	v_lshl_add_u32 v66, v65, 13, 0
	v_lshlrev_b32_e32 v67, 1, v64
	v_mov_b32_e32 v68, 0
	s_mov_b32 s2, 0
	v_mov_b32_e32 v35, v34
	v_mov_b32_e32 v62, v34
	v_mov_b32_e32 v63, v34
	v_mov_b32_e32 v60, v34
	v_mov_b32_e32 v61, v34
	v_mov_b32_e32 v58, v34
	v_mov_b32_e32 v59, v34
	v_mov_b32_e32 v56, v34
	v_mov_b32_e32 v57, v34
	v_mov_b32_e32 v54, v34
	v_mov_b32_e32 v55, v34
	v_mov_b32_e32 v50, v34
	v_mov_b32_e32 v51, v34
	v_mov_b32_e32 v46, v34
	v_mov_b32_e32 v47, v34
	v_mov_b32_e32 v32, v34
	v_mov_b32_e32 v33, v34
	v_mov_b32_e32 v52, v34
	v_mov_b32_e32 v53, v34
	v_mov_b32_e32 v48, v34
	v_mov_b32_e32 v49, v34
	v_mov_b32_e32 v44, v34
	v_mov_b32_e32 v45, v34
	v_mov_b32_e32 v42, v34
	v_mov_b32_e32 v43, v34
	v_mov_b32_e32 v40, v34
	v_mov_b32_e32 v41, v34
	v_mov_b32_e32 v38, v34
	v_mov_b32_e32 v39, v34
	v_mov_b32_e32 v36, v34
	v_mov_b32_e32 v37, v34
	s_waitcnt lgkmcnt(0)
	s_barrier
	v_mov_b32_e32 v76, 0
	v_mov_b32_e32 v77, v76
	v_mov_b32_e32 v78, v76
	v_mov_b32_e32 v79, v76
	v_mov_b32_e32 v80, v76
	v_mov_b32_e32 v81, v76
	v_mov_b32_e32 v82, v76
	v_mov_b32_e32 v83, v76
	v_mov_b32_e32 v84, v76
	v_mov_b32_e32 v85, v76
	v_mov_b32_e32 v86, v76
	v_mov_b32_e32 v87, v76
	v_mov_b32_e32 v88, v76
	v_mov_b32_e32 v89, v76
	v_mov_b32_e32 v90, v76
	v_mov_b32_e32 v91, v76
	v_mov_b32_e32 v92, v76
	v_mov_b32_e32 v93, v76
	v_mov_b32_e32 v94, v76
	v_mov_b32_e32 v95, v76
	v_mov_b32_e32 v96, v76
	v_mov_b32_e32 v97, v76
	v_mov_b32_e32 v98, v76
	v_mov_b32_e32 v99, v76
	v_mov_b32_e32 v100, v76
	v_mov_b32_e32 v101, v76
	v_mov_b32_e32 v102, v76
	v_mov_b32_e32 v103, v76
	v_mov_b32_e32 v104, v76
	v_mov_b32_e32 v105, v76
	v_mov_b32_e32 v106, v76
	v_mov_b32_e32 v107, v76
	v_mov_b32_e32 v108, v76
	v_mov_b32_e32 v109, v76
	v_mov_b32_e32 v110, v76
	v_mov_b32_e32 v111, v76
	v_mov_b32_e32 v112, v76
	v_mov_b32_e32 v113, v76
	v_mov_b32_e32 v114, v76
	v_mov_b32_e32 v115, v76
	v_mov_b32_e32 v116, v76
	v_mov_b32_e32 v117, v76
	v_mov_b32_e32 v118, v76
	v_mov_b32_e32 v119, v76
	v_mov_b32_e32 v120, v76
	v_mov_b32_e32 v121, v76
	v_mov_b32_e32 v122, v76
	v_mov_b32_e32 v123, v76
	v_mov_b32_e32 v124, v76
	v_mov_b32_e32 v125, v76
	v_mov_b32_e32 v126, v76
	v_mov_b32_e32 v127, v76
	v_mov_b32_e32 v128, v76
	v_mov_b32_e32 v129, v76
	v_mov_b32_e32 v130, v76
	v_mov_b32_e32 v131, v76
	v_mov_b32_e32 v132, v76
	v_mov_b32_e32 v133, v76
	v_mov_b32_e32 v134, v76
	v_mov_b32_e32 v135, v76
	v_mov_b32_e32 v136, v76
	v_mov_b32_e32 v137, v76
	v_mov_b32_e32 v138, v76
	v_mov_b32_e32 v139, v76
; __device__ __forceinline__ unsigned cvt_pk_bf16(float lo, float hi) { unsigned r; asm("v_cvt_pk_bf16_f32 %0, %1, %2" : "=v"(r) : "v"(lo), "v"(hi)); return r; }
; __device__ __forceinline__ void winbf_task(LAS unsigned char* lds, const float* w_in_l, bf16_t* dst, int task) {
;     ...
;     for (int c = 0; c < 128; ++c) { const int idx = (c * cp) & 127; const float vc = tc[idx], vs = ts[idx];
; #pragma unroll
;         for (int kk = 0; kk < 16; ++kk) { const float w = Wt[(kq * 16 + kk) * 128 + c]; aC[kk] += w * vc; aS[kk] += w * vs; } }
;     bf16_t* dc = dst + (size_t)(g * 128 + cp) * 2048 + k0 + kq * 16; bf16_t* ds = dst + (size_t)(512 + g * 128 + cp) * 2048 + k0 + kq * 16;
;     u32x4 w; w.x = cvt_pk_bf16(aC[0], aC[1]); w.y = cvt_pk_bf16(aC[2], aC[3]); w.z = cvt_pk_bf16(aC[4], aC[5]); w.w = cvt_pk_bf16(aC[6], aC[7]); *(u32x4*)dc = w;
;     w.x = cvt_pk_bf16(aC[8], aC[9]); w.y = cvt_pk_bf16(aC[10], aC[11]); w.z = cvt_pk_bf16(aC[12], aC[13]); w.w = cvt_pk_bf16(aC[14], aC[15]); *(u32x4*)(dc + 8) = w;
;     w.x = cvt_pk_bf16(aS[0], aS[1]); w.y = cvt_pk_bf16(aS[2], aS[3]); w.z = cvt_pk_bf16(aS[4], aS[5]); w.w = cvt_pk_bf16(aS[6], aS[7]); *(u32x4*)ds = w;
;     w.x = cvt_pk_bf16(aS[8], aS[9]); w.y = cvt_pk_bf16(aS[10], aS[11]); w.z = cvt_pk_bf16(aS[12], aS[13]); w.w = cvt_pk_bf16(aS[14], aS[15]); *(u32x4*)(ds + 8) = w;
.Lwb_loop:
	v_and_b32_e32 v74, 0x7e, v68
	v_lshlrev_b32_e32 v74, 2, v74
	v_add_u32_e32 v75, v64, v68
	v_and_b32_e32 v75, 0x7f, v75
	v_lshlrev_b32_e32 v75, 2, v75
	v_add_u32_e32 v30, s2, v66
	ds_read_b32 v70, v74 offset:32768
	ds_read_b32 v71, v75 offset:32768
	ds_read_b32 v72, v74 offset:33280
	ds_read_b32 v73, v75 offset:33280
	ds_read2st64_b64 v[0:3], v30 offset1:1
	ds_read2st64_b64 v[4:7], v30 offset0:2 offset1:3
	ds_read2st64_b64 v[8:11], v30 offset0:4 offset1:5
	ds_read2st64_b64 v[12:15], v30 offset0:6 offset1:7
	ds_read2st64_b64 v[16:19], v30 offset0:8 offset1:9
	ds_read2st64_b64 v[20:23], v30 offset0:10 offset1:11
	ds_read2st64_b64 v[24:27], v30 offset0:12 offset1:13
	ds_read2st64_b64 v[28:31], v30 offset0:14 offset1:15
	s_add_i32 s2, s2, 8
	v_add_u32_e32 v68, v68, v67
	s_waitcnt lgkmcnt(7)
	v_pk_fma_f32 v[76:77], v[70:71], v[0:1], v[76:77]
	v_pk_fma_f32 v[108:109], v[72:73], v[0:1], v[108:109]
	v_pk_fma_f32 v[78:79], v[70:71], v[2:3], v[78:79]
	v_pk_fma_f32 v[110:111], v[72:73], v[2:3], v[110:111]
	s_waitcnt lgkmcnt(6)
	v_pk_fma_f32 v[80:81], v[70:71], v[4:5], v[80:81]
	v_pk_fma_f32 v[112:113], v[72:73], v[4:5], v[112:113]
	v_pk_fma_f32 v[82:83], v[70:71], v[6:7], v[82:83]
	v_pk_fma_f32 v[114:115], v[72:73], v[6:7], v[114:115]
	s_waitcnt lgkmcnt(5)
	v_pk_fma_f32 v[84:85], v[70:71], v[8:9], v[84:85]
	v_pk_fma_f32 v[116:117], v[72:73], v[8:9], v[116:117]
	v_pk_fma_f32 v[86:87], v[70:71], v[10:11], v[86:87]
	v_pk_fma_f32 v[118:119], v[72:73], v[10:11], v[118:119]
	s_waitcnt lgkmcnt(4)
	v_pk_fma_f32 v[88:89], v[70:71], v[12:13], v[88:89]
	v_pk_fma_f32 v[120:121], v[72:73], v[12:13], v[120:121]
	v_pk_fma_f32 v[90:91], v[70:71], v[14:15], v[90:91]
	v_pk_fma_f32 v[122:123], v[72:73], v[14:15], v[122:123]
	s_waitcnt lgkmcnt(3)
	v_pk_fma_f32 v[92:93], v[70:71], v[16:17], v[92:93]
	v_pk_fma_f32 v[124:125], v[72:73], v[16:17], v[124:125]
	v_pk_fma_f32 v[94:95], v[70:71], v[18:19], v[94:95]
	v_pk_fma_f32 v[126:127], v[72:73], v[18:19], v[126:127]
	s_waitcnt lgkmcnt(2)
	v_pk_fma_f32 v[96:97], v[70:71], v[20:21], v[96:97]
	v_pk_fma_f32 v[128:129], v[72:73], v[20:21], v[128:129]
	v_pk_fma_f32 v[98:99], v[70:71], v[22:23], v[98:99]
	v_pk_fma_f32 v[130:131], v[72:73], v[22:23], v[130:131]
	s_waitcnt lgkmcnt(1)
	v_pk_fma_f32 v[100:101], v[70:71], v[24:25], v[100:101]
	v_pk_fma_f32 v[132:133], v[72:73], v[24:25], v[132:133]
	v_pk_fma_f32 v[102:103], v[70:71], v[26:27], v[102:103]
	v_pk_fma_f32 v[134:135], v[72:73], v[26:27], v[134:135]
	s_waitcnt lgkmcnt(0)
	v_pk_fma_f32 v[104:105], v[70:71], v[28:29], v[104:105]
	v_pk_fma_f32 v[136:137], v[72:73], v[28:29], v[136:137]
	v_pk_fma_f32 v[106:107], v[70:71], v[30:31], v[106:107]
	v_pk_fma_f32 v[138:139], v[72:73], v[30:31], v[138:139]
	s_cmpk_lg_i32 s2, 0x200
	s_cbranch_scc1 .Lwb_loop
	v_add_f32_e32 v62, v76, v77
	v_add_f32_e32 v63, v78, v79
	v_add_f32_e32 v52, v108, v109
	v_add_f32_e32 v53, v110, v111
	v_add_f32_e32 v60, v80, v81
	v_add_f32_e32 v61, v82, v83
	v_add_f32_e32 v48, v112, v113
	v_add_f32_e32 v49, v114, v115
	v_add_f32_e32 v58, v84, v85
	v_add_f32_e32 v59, v86, v87
	v_add_f32_e32 v44, v116, v117
	v_add_f32_e32 v45, v118, v119
	v_add_f32_e32 v56, v88, v89
	v_add_f32_e32 v57, v90, v91
	v_add_f32_e32 v42, v120, v121
	v_add_f32_e32 v43, v122, v123
	v_add_f32_e32 v54, v92, v93
	v_add_f32_e32 v55, v94, v95
	v_add_f32_e32 v40, v124, v125
	v_add_f32_e32 v41, v126, v127
	v_add_f32_e32 v50, v96, v97
	v_add_f32_e32 v51, v98, v99
	v_add_f32_e32 v38, v128, v129
	v_add_f32_e32 v39, v130, v131
	v_add_f32_e32 v46, v100, v101
	v_add_f32_e32 v47, v102, v103
	v_add_f32_e32 v36, v132, v133
	v_add_f32_e32 v37, v134, v135
	v_add_f32_e32 v34, v104, v105
	v_add_f32_e32 v35, v106, v107
	v_add_f32_e32 v32, v136, v137
	v_add_f32_e32 v33, v138, v139
	v_and_b32_e32 v0, 0x7f, v64
	v_or_b32_e32 v0, s31, v0
	v_lshlrev_b32_e32 v172, 12, v0
	v_lshl_add_u64 v[0:1], s[34:35], 0, v[172:173]
	s_ashr_i32 s37, s36, 31
	v_lshlrev_b32_e32 v2, 4, v65
	v_lshl_add_u64 v[0:1], s[36:37], 1, v[0:1]
	v_ashrrev_i32_e32 v3, 31, v2
	v_lshl_add_u64 v[4:5], v[2:3], 1, v[0:1]
	s_mov_b64 s[36:37], 0x200000
	v_cvt_pk_bf16_f32 v0, v62, v63
	v_cvt_pk_bf16_f32 v1, v60, v61
	v_cvt_pk_bf16_f32 v2, v58, v59
	v_cvt_pk_bf16_f32 v3, v56, v57
	v_lshl_add_u64 v[6:7], v[4:5], 0, s[36:37]
	flat_store_dwordx4 v[4:5], v[0:3]
	s_add_i32 s0, s0, s42
	s_cmpk_gt_i32 s0, 0x7f
	v_cvt_pk_bf16_f32 v0, v54, v55
	v_cvt_pk_bf16_f32 v1, v50, v51
	v_cvt_pk_bf16_f32 v2, v46, v47
	v_cvt_pk_bf16_f32 v3, v34, v35
	flat_store_dwordx4 v[4:5], v[0:3] offset:16
	v_add_co_u32_e32 v4, vcc, s61, v4
	s_nop 0
	v_cvt_pk_bf16_f32 v0, v52, v53
	v_cvt_pk_bf16_f32 v1, v48, v49
	v_cvt_pk_bf16_f32 v2, v44, v45
	v_cvt_pk_bf16_f32 v3, v42, v43
	s_nop 0
	v_addc_co_u32_e32 v5, vcc, 0, v5, vcc
	flat_store_dwordx4 v[4:5], v[0:3]
	s_nop 1
	v_cvt_pk_bf16_f32 v0, v40, v41
	v_cvt_pk_bf16_f32 v1, v38, v39
	v_cvt_pk_bf16_f32 v2, v36, v37
	v_cvt_pk_bf16_f32 v3, v32, v33
	flat_store_dwordx4 v[6:7], v[0:3] offset:16
	s_waitcnt lgkmcnt(0)
	s_barrier
	s_cbranch_scc0 .LBB0_66

; #define LAS __attribute__((address_space(3)))
; __device__ __forceinline__ int tid_l() { int t = threadIdx.x; asm volatile("" : "+v"(t)); return t; }
; __device__ __forceinline__ float bf_lo(unsigned w) { return __uint_as_float(w << 16); }
; __device__ __forceinline__ float bf_hi(unsigned w) { return __uint_as_float(w & 0xffff0000u); }
; __device__ __forceinline__ bf16_t f2bf(float f) { return (bf16_t)(cvt_pk_bf16(f, 0.f) & 0xffffu); }
; __device__ __forceinline__ void gmlp_task(LAS unsigned char* lds, const bf16_t* zina, const bf16_t* wsb, const float* vg, const float* bs, bf16_t* y, int task) {
;     const int tid = tid_l(), lane = tid & 63, wid = tid >> 6, fr = lane & 15, fq = lane >> 4;
;     const int cidx = task / 6, h = task - cidx * 6, t0 = cidx * 128;
;     LAS bf16_t* vT = (LAS bf16_t*)lds;
;     { const int k = tid >> 2, dq = (tid & 3) * 32;
;       const bf16_t* src = zina + (size_t)(t0 + k) * 1536 + 768 + h * 128 + dq;
;       u32x4 w[4]; float ss = 0.f;
; #pragma unroll
;       for (int q = 0; q < 4; ++q) { w[q] = *(const u32x4*)(src + q * 8);
; #pragma unroll
;           for (int e = 0; e < 4; ++e) { const float a0 = bf_lo(w[q][e]), a1 = bf_hi(w[q][e]); ss += a0 * a0 + a1 * a1; } }
;       ss += __shfl_xor(ss, 1); ss += __shfl_xor(ss, 2);
;       const float r = 1.0f / sqrtf(ss * (1.0f / 128.0f) + EPS);
; #pragma unroll
;       for (int q = 0; q < 4; ++q)
; #pragma unroll
;           for (int e = 0; e < 4; ++e) { const int d = dq + q * 8 + e * 2;
;               vT[d * 136 + k] = f2bf(bf_lo(w[q][e]) * r * vg[h * 128 + d]); vT[(d + 1) * 136 + k] = f2bf(bf_hi(w[q][e]) * r * vg[h * 128 + d + 1]); } }
;     __syncthreads();
.Lgm_setup:
	v_lshrrev_b32_e32 v159, 2, v175
	v_and_b32_e32 v160, 3, v175
	v_lshlrev_b32_e32 v161, 6, v160
	v_mad_u32_u24 v148, v159, s88, v161
	v_lshlrev_b32_e32 v149, 7, v160
	v_mul_u32_u24_e32 v161, 0x2220, v160
	v_lshl_add_u32 v150, v159, 1, v161
	v_and_b32_e32 v159, 15, v175
	v_bfe_u32 v160, v175, 4, 2
	v_lshrrev_b32_e32 v161, 7, v175
	v_lshl_add_u32 v161, v161, 5, v159
	v_bfe_u32 v162, v175, 6, 1
	v_lshlrev_b32_e32 v162, 6, v162
	v_lshlrev_b32_e32 v163, 4, v160
	v_lshl_add_u32 v151, v161, 8, v163
	v_add_u32_e32 v152, 0x1000, v151
	v_add_u32_e32 v164, v162, v159
	v_mul_u32_u24_e32 v164, 0x110, v164
	v_add3_u32 v153, v164, v163, v162
	v_lshlrev_b32_e32 v164, 3, v160
	v_lshl_add_u32 v164, v162, 1, v164
	v_mad_u32_u24 v154, v161, s88, v164
	v_add_u32_e32 v155, 0xc000, v154
	v_lshlrev_b32_e32 v156, 2, v161
	v_lshl_add_u32 v157, v161, 12, v164
	v_add_u32_e32 v158, 0x10000, v157
	s_mul_hi_u32 s34, s0, 0xaaaaaaab
	s_lshr_b32 s34, s34, 2
	s_mul_i32 s35, s34, 6
	s_sub_i32 s35, s0, s35
	s_mul_i32 s36, s34, 0x60000
	s_lshl_b32 s37, s35, 8
	s_add_i32 s36, s36, s37
	v_add_u32_e32 v166, s36, v148
	global_load_dwordx4 v[0:3], v166, s[42:43] offset:1536
	global_load_dwordx4 v[4:7], v166, s[42:43] offset:1552
	global_load_dwordx4 v[8:11], v166, s[42:43] offset:1568
	global_load_dwordx4 v[12:15], v166, s[42:43] offset:1584
.Lgm_task:
	s_mul_hi_u32 s34, s0, 0xaaaaaaab
	s_lshr_b32 s34, s34, 2
	s_mul_i32 s35, s34, 6
	s_sub_i32 s35, s0, s35
	s_mul_i32 s36, s34, 0x60000
	s_lshl_b32 s37, s35, 8
	s_add_i32 s36, s36, s37
	s_lshl_b32 s37, s35, 9
	v_add_u32_e32 v167, s37, v149
	global_load_dwordx4 v[48:51], v167, s[46:47]
	global_load_dwordx4 v[52:55], v167, s[46:47] offset:16
	global_load_dwordx4 v[56:59], v167, s[46:47] offset:32
	global_load_dwordx4 v[60:63], v167, s[46:47] offset:48
	global_load_dwordx4 v[64:67], v167, s[46:47] offset:64
	global_load_dwordx4 v[68:71], v167, s[46:47] offset:80
	global_load_dwordx4 v[72:75], v167, s[46:47] offset:96
	global_load_dwordx4 v[76:79], v167, s[46:47] offset:112
	s_lshl_b32 s38, s35, 15
	v_add_u32_e32 v168, s38, v151
	v_add_u32_e32 v169, s38, v152
	global_load_dwordx4 v[80:83], v168, s[44:45]
	global_load_dwordx4 v[84:87], v168, s[44:45] offset:64
	global_load_dwordx4 v[88:91], v168, s[44:45] offset:128
	global_load_dwordx4 v[92:95], v168, s[44:45] offset:192
	global_load_dwordx4 v[96:99], v169, s[44:45]
	global_load_dwordx4 v[100:103], v169, s[44:45] offset:64
	global_load_dwordx4 v[104:107], v169, s[44:45] offset:128
	global_load_dwordx4 v[108:111], v169, s[44:45] offset:192
	v_add_u32_e32 v166, s36, v154
	v_add_u32_e32 v168, s36, v155
	global_load_dwordx2 v[112:113], v166, s[42:43]
	global_load_dwordx2 v[114:115], v166, s[42:43] offset:32
	global_load_dwordx2 v[116:117], v166, s[42:43] offset:64
	global_load_dwordx2 v[118:119], v166, s[42:43] offset:96
	global_load_dwordx2 v[120:121], v168, s[42:43]
	global_load_dwordx2 v[122:123], v168, s[42:43] offset:32
	global_load_dwordx2 v[124:125], v168, s[42:43] offset:64
	global_load_dwordx2 v[126:127], v168, s[42:43] offset:96
	v_add_u32_e32 v167, s37, v156
	global_load_dword v146, v167, s[48:49]
	global_load_dword v147, v167, s[48:49] offset:64
	s_waitcnt vmcnt(26)
	v_lshlrev_b32_e32 v16, 16, v0
	v_and_b32_e32 v17, 0xffff0000, v0
	v_lshlrev_b32_e32 v18, 16, v1
	v_and_b32_e32 v19, 0xffff0000, v1
	v_lshlrev_b32_e32 v20, 16, v2
	v_and_b32_e32 v21, 0xffff0000, v2
	v_lshlrev_b32_e32 v22, 16, v3
	v_and_b32_e32 v23, 0xffff0000, v3
	v_lshlrev_b32_e32 v24, 16, v4
	v_and_b32_e32 v25, 0xffff0000, v4
	v_lshlrev_b32_e32 v26, 16, v5
	v_and_b32_e32 v27, 0xffff0000, v5
	v_lshlrev_b32_e32 v28, 16, v6
	v_and_b32_e32 v29, 0xffff0000, v6
	v_lshlrev_b32_e32 v30, 16, v7
	v_and_b32_e32 v31, 0xffff0000, v7
	v_lshlrev_b32_e32 v32, 16, v8
	v_and_b32_e32 v33, 0xffff0000, v8
	v_lshlrev_b32_e32 v34, 16, v9
	v_and_b32_e32 v35, 0xffff0000, v9
	v_lshlrev_b32_e32 v36, 16, v10
	v_and_b32_e32 v37, 0xffff0000, v10
	v_lshlrev_b32_e32 v38, 16, v11
	v_and_b32_e32 v39, 0xffff0000, v11
	v_lshlrev_b32_e32 v40, 16, v12
	v_and_b32_e32 v41, 0xffff0000, v12
	v_lshlrev_b32_e32 v42, 16, v13
	v_and_b32_e32 v43, 0xffff0000, v13
	v_lshlrev_b32_e32 v44, 16, v14
	v_and_b32_e32 v45, 0xffff0000, v14
	v_lshlrev_b32_e32 v46, 16, v15
	v_and_b32_e32 v47, 0xffff0000, v15
	s_add_i32 s28, s0, s2
	s_cmp_lt_i32 s28, s33
	s_cselect_b32 s28, s28, s0
	s_mul_hi_u32 s29, s28, 0xaaaaaaab
	s_lshr_b32 s29, s29, 2
	s_mul_i32 s37, s29, 6
	s_sub_i32 s37, s28, s37
	s_mul_i32 s29, s29, 0x60000
	s_lshl_b32 s37, s37, 8
	s_add_i32 s29, s29, s37
	v_add_u32_e32 v166, s29, v148
	global_load_dwordx4 v[0:3], v166, s[42:43] offset:1536
	global_load_dwordx4 v[4:7], v166, s[42:43] offset:1552
	global_load_dwordx4 v[8:11], v166, s[42:43] offset:1568
	global_load_dwordx4 v[12:15], v166, s[42:43] offset:1584
	v_mul_f32_e32 v159, v16, v16
	v_fmac_f32_e32 v159, v17, v17
	v_fmac_f32_e32 v159, v18, v18
	v_fmac_f32_e32 v159, v19, v19
	v_fmac_f32_e32 v159, v20, v20
	v_fmac_f32_e32 v159, v21, v21
	v_fmac_f32_e32 v159, v22, v22
	v_fmac_f32_e32 v159, v23, v23
	v_fmac_f32_e32 v159, v24, v24
	v_fmac_f32_e32 v159, v25, v25
	v_fmac_f32_e32 v159, v26, v26
	v_fmac_f32_e32 v159, v27, v27
	v_fmac_f32_e32 v159, v28, v28
	v_fmac_f32_e32 v159, v29, v29
	v_fmac_f32_e32 v159, v30, v30
	v_fmac_f32_e32 v159, v31, v31
	v_fmac_f32_e32 v159, v32, v32
	v_fmac_f32_e32 v159, v33, v33
	v_fmac_f32_e32 v159, v34, v34
	v_fmac_f32_e32 v159, v35, v35
	v_fmac_f32_e32 v159, v36, v36
	v_fmac_f32_e32 v159, v37, v37
	v_fmac_f32_e32 v159, v38, v38
	v_fmac_f32_e32 v159, v39, v39
	v_fmac_f32_e32 v159, v40, v40
	v_fmac_f32_e32 v159, v41, v41
	v_fmac_f32_e32 v159, v42, v42
	v_fmac_f32_e32 v159, v43, v43
	v_fmac_f32_e32 v159, v44, v44
	v_fmac_f32_e32 v159, v45, v45
	v_fmac_f32_e32 v159, v46, v46
	v_fmac_f32_e32 v159, v47, v47
	s_nop 1
	v_add_f32_dpp v159, v159, v159 quad_perm:[1,0,3,2] row_mask:0xf bank_mask:0xf
	s_nop 1
	v_add_f32_dpp v159, v159, v159 quad_perm:[2,3,0,1] row_mask:0xf bank_mask:0xf
	v_fmamk_f32 v159, v159, 0x3c000000, v222
	v_cmp_gt_f32_e32 vcc, s89, v159
	v_mul_f32_e32 v160, 0x4f800000, v159
	s_nop 0
	v_cndmask_b32_e32 v159, v159, v160, vcc
	v_sqrt_f32_e32 v160, v159
	s_nop 0
	v_add_u32_e32 v161, -1, v160
	v_fma_f32 v162, -v161, v160, v159
	v_cmp_ge_f32_e64 s[38:39], 0, v162
	v_add_u32_e32 v162, 1, v160
	s_nop 0
	v_cndmask_b32_e64 v161, v160, v161, s[38:39]
	v_fma_f32 v160, -v162, v160, v159
	v_cmp_lt_f32_e64 s[38:39], 0, v160
	s_nop 1
	v_cndmask_b32_e64 v160, v161, v162, s[38:39]
	v_mul_f32_e32 v161, 0x37800000, v160
	v_cndmask_b32_e32 v160, v160, v161, vcc
	v_cmp_class_f32_e32 vcc, v159, v223
	s_nop 1
	v_cndmask_b32_e32 v159, v160, v159, vcc
	v_div_scale_f32 v160, s[38:39], v159, v159, 1.0
	v_rcp_f32_e32 v161, v160
	s_nop 0
	v_fma_f32 v162, -v160, v161, 1.0
	v_fmac_f32_e32 v161, v162, v161
	v_div_scale_f32 v162, vcc, 1.0, v159, 1.0
	v_mul_f32_e32 v163, v162, v161
	v_fma_f32 v164, -v160, v163, v162
	v_fmac_f32_e32 v163, v164, v161
	v_fma_f32 v160, -v160, v163, v162
	v_div_fmas_f32 v160, v160, v161, v163
	v_div_fixup_f32 v165, v160, v159, 1.0
	s_waitcnt vmcnt(22)
; #define LAS __attribute__((address_space(3)))
; __device__ __forceinline__ float bf_lo(unsigned w) { return __uint_as_float(w << 16); }
; __device__ __forceinline__ float bf_hi(unsigned w) { return __uint_as_float(w & 0xffff0000u); }
; __device__ __forceinline__ bf16_t f2bf(float f) { return (bf16_t)(cvt_pk_bf16(f, 0.f) & 0xffffu); }
; __device__ __forceinline__ void gmlp_task(LAS unsigned char* lds, const bf16_t* zina, const bf16_t* wsb, const float* vg, const float* bs, bf16_t* y, int task) {
;     ...
; #pragma unroll
;       for (int q = 0; q < 4; ++q)
; #pragma unroll
;           for (int e = 0; e < 4; ++e) { const int d = dq + q * 8 + e * 2;
;               vT[d * 136 + k] = f2bf(bf_lo(w[q][e]) * r * vg[h * 128 + d]); vT[(d + 1) * 136 + k] = f2bf(bf_hi(w[q][e]) * r * vg[h * 128 + d + 1]); } }
;     __syncthreads();
;     const int q0 = (wid >> 1) * 32, d0 = (wid & 1) * 64;
;     f32x4 acc[2][4];
; #pragma unroll
;     for (int mq = 0; mq < 2; ++mq)
; #pragma unroll
;         for (int nd = 0; nd < 4; ++nd) acc[mq][nd] = (f32x4){0.f, 0.f, 0.f, 0.f};
; #pragma unroll
;     for (int ks = 0; ks < 4; ++ks) {
;         bf16x8 af[2], bfr[4];
; #pragma unroll
;         for (int mq = 0; mq < 2; ++mq) af[mq] = *(const bf16x8*)(wsb + (size_t)(h * 128 + q0 + mq * 16 + fr) * 128 + ks * 32 + fq * 8);
; #pragma unroll
;         for (int nd = 0; nd < 4; ++nd) bfr[nd] = *(const LAS bf16x8*)(vT + (d0 + nd * 16 + fr) * 136 + ks * 32 + fq * 8);
	v_mul_f32_e32 v16, v165, v16
	v_mul_f32_e32 v16, v48, v16
	v_cvt_pk_bf16_f32 v16, v16, v173
	ds_write_b16 v150, v16
	v_mul_f32_e32 v17, v165, v17
	v_mul_f32_e32 v17, v49, v17
	v_cvt_pk_bf16_f32 v17, v17, v173
	ds_write_b16 v150, v17 offset:272
	v_mul_f32_e32 v18, v165, v18
	v_mul_f32_e32 v18, v50, v18
	v_cvt_pk_bf16_f32 v18, v18, v173
	ds_write_b16 v150, v18 offset:544
	v_mul_f32_e32 v19, v165, v19
	v_mul_f32_e32 v19, v51, v19
	v_cvt_pk_bf16_f32 v19, v19, v173
	ds_write_b16 v150, v19 offset:816
	v_mul_f32_e32 v20, v165, v20
	v_mul_f32_e32 v20, v52, v20
	v_cvt_pk_bf16_f32 v20, v20, v173
	ds_write_b16 v150, v20 offset:1088
	v_mul_f32_e32 v21, v165, v21
	v_mul_f32_e32 v21, v53, v21
	v_cvt_pk_bf16_f32 v21, v21, v173
	ds_write_b16 v150, v21 offset:1360
	v_mul_f32_e32 v22, v165, v22
	v_mul_f32_e32 v22, v54, v22
	v_cvt_pk_bf16_f32 v22, v22, v173
	ds_write_b16 v150, v22 offset:1632
	v_mul_f32_e32 v23, v165, v23
	v_mul_f32_e32 v23, v55, v23
	v_cvt_pk_bf16_f32 v23, v23, v173
	ds_write_b16 v150, v23 offset:1904
	v_mul_f32_e32 v24, v165, v24
	v_mul_f32_e32 v24, v56, v24
	v_cvt_pk_bf16_f32 v24, v24, v173
	ds_write_b16 v150, v24 offset:2176
	v_mul_f32_e32 v25, v165, v25
	v_mul_f32_e32 v25, v57, v25
	v_cvt_pk_bf16_f32 v25, v25, v173
	ds_write_b16 v150, v25 offset:2448
	v_mul_f32_e32 v26, v165, v26
	v_mul_f32_e32 v26, v58, v26
	v_cvt_pk_bf16_f32 v26, v26, v173
	ds_write_b16 v150, v26 offset:2720
	v_mul_f32_e32 v27, v165, v27
	v_mul_f32_e32 v27, v59, v27
	v_cvt_pk_bf16_f32 v27, v27, v173
	ds_write_b16 v150, v27 offset:2992
	v_mul_f32_e32 v28, v165, v28
	v_mul_f32_e32 v28, v60, v28
	v_cvt_pk_bf16_f32 v28, v28, v173
	ds_write_b16 v150, v28 offset:3264
	v_mul_f32_e32 v29, v165, v29
	v_mul_f32_e32 v29, v61, v29
	v_cvt_pk_bf16_f32 v29, v29, v173
	ds_write_b16 v150, v29 offset:3536
	v_mul_f32_e32 v30, v165, v30
	v_mul_f32_e32 v30, v62, v30
	v_cvt_pk_bf16_f32 v30, v30, v173
	ds_write_b16 v150, v30 offset:3808
	v_mul_f32_e32 v31, v165, v31
	v_mul_f32_e32 v31, v63, v31
	v_cvt_pk_bf16_f32 v31, v31, v173
	ds_write_b16 v150, v31 offset:4080
	v_mul_f32_e32 v32, v165, v32
	v_mul_f32_e32 v32, v64, v32
	v_cvt_pk_bf16_f32 v32, v32, v173
	ds_write_b16 v150, v32 offset:4352
	v_mul_f32_e32 v33, v165, v33
	v_mul_f32_e32 v33, v65, v33
	v_cvt_pk_bf16_f32 v33, v33, v173
	ds_write_b16 v150, v33 offset:4624
	v_mul_f32_e32 v34, v165, v34
	v_mul_f32_e32 v34, v66, v34
	v_cvt_pk_bf16_f32 v34, v34, v173
	ds_write_b16 v150, v34 offset:4896
	v_mul_f32_e32 v35, v165, v35
	v_mul_f32_e32 v35, v67, v35
	v_cvt_pk_bf16_f32 v35, v35, v173
	ds_write_b16 v150, v35 offset:5168
	v_mul_f32_e32 v36, v165, v36
	v_mul_f32_e32 v36, v68, v36
	v_cvt_pk_bf16_f32 v36, v36, v173
	ds_write_b16 v150, v36 offset:5440
	v_mul_f32_e32 v37, v165, v37
	v_mul_f32_e32 v37, v69, v37
	v_cvt_pk_bf16_f32 v37, v37, v173
	ds_write_b16 v150, v37 offset:5712
	v_mul_f32_e32 v38, v165, v38
	v_mul_f32_e32 v38, v70, v38
	v_cvt_pk_bf16_f32 v38, v38, v173
	ds_write_b16 v150, v38 offset:5984
	v_mul_f32_e32 v39, v165, v39
	v_mul_f32_e32 v39, v71, v39
	v_cvt_pk_bf16_f32 v39, v39, v173
	ds_write_b16 v150, v39 offset:6256
	v_mul_f32_e32 v40, v165, v40
	v_mul_f32_e32 v40, v72, v40
	v_cvt_pk_bf16_f32 v40, v40, v173
	ds_write_b16 v150, v40 offset:6528
	v_mul_f32_e32 v41, v165, v41
	v_mul_f32_e32 v41, v73, v41
	v_cvt_pk_bf16_f32 v41, v41, v173
	ds_write_b16 v150, v41 offset:6800
	v_mul_f32_e32 v42, v165, v42
	v_mul_f32_e32 v42, v74, v42
	v_cvt_pk_bf16_f32 v42, v42, v173
	ds_write_b16 v150, v42 offset:7072
	v_mul_f32_e32 v43, v165, v43
	v_mul_f32_e32 v43, v75, v43
	v_cvt_pk_bf16_f32 v43, v43, v173
	ds_write_b16 v150, v43 offset:7344
	v_mul_f32_e32 v44, v165, v44
	v_mul_f32_e32 v44, v76, v44
	v_cvt_pk_bf16_f32 v44, v44, v173
	ds_write_b16 v150, v44 offset:7616
	v_mul_f32_e32 v45, v165, v45
	v_mul_f32_e32 v45, v77, v45
	v_cvt_pk_bf16_f32 v45, v45, v173
	ds_write_b16 v150, v45 offset:7888
	v_mul_f32_e32 v46, v165, v46
	v_mul_f32_e32 v46, v78, v46
	v_cvt_pk_bf16_f32 v46, v46, v173
	ds_write_b16 v150, v46 offset:8160
	v_mul_f32_e32 v47, v165, v47
	v_mul_f32_e32 v47, v79, v47
	v_cvt_pk_bf16_f32 v47, v47, v173
	ds_write_b16 v150, v47 offset:8432
	s_waitcnt lgkmcnt(0)
	s_barrier
	ds_read_b128 v[16:19], v153
	ds_read_b128 v[20:23], v153 offset:4352
	ds_read_b128 v[24:27], v153 offset:8736
	ds_read_b128 v[28:31], v153 offset:13088
	ds_read_b128 v[32:35], v153 offset:64
	ds_read_b128 v[36:39], v153 offset:4416
	ds_read_b128 v[40:43], v153 offset:8800
	ds_read_b128 v[44:47], v153 offset:13152
	s_waitcnt vmcnt(14) lgkmcnt(4)
	v_mfma_f32_16x16x32_bf16 v[198:201], v[16:19], v[80:83], 0
	v_mfma_f32_16x16x32_bf16 v[202:205], v[20:23], v[80:83], 0
	v_mfma_f32_16x16x32_bf16 v[206:209], v[24:27], v[80:83], 0
	v_mfma_f32_16x16x32_bf16 v[210:213], v[28:31], v[80:83], 0
	v_mfma_f32_16x16x32_bf16 v[214:217], v[16:19], v[96:99], 0
	v_mfma_f32_16x16x32_bf16 v[218:221], v[20:23], v[96:99], 0
	v_mfma_f32_16x16x32_bf16 v[228:231], v[24:27], v[96:99], 0
	v_mfma_f32_16x16x32_bf16 v[232:235], v[28:31], v[96:99], 0
	ds_read_b128 v[16:19], v153 offset:128
	ds_read_b128 v[20:23], v153 offset:4480
	ds_read_b128 v[24:27], v153 offset:8864
	ds_read_b128 v[28:31], v153 offset:13216
	s_waitcnt lgkmcnt(4)
	v_mfma_f32_16x16x32_bf16 v[198:201], v[32:35], v[84:87], v[198:201]
	v_mfma_f32_16x16x32_bf16 v[202:205], v[36:39], v[84:87], v[202:205]
	v_mfma_f32_16x16x32_bf16 v[206:209], v[40:43], v[84:87], v[206:209]
	v_mfma_f32_16x16x32_bf16 v[210:213], v[44:47], v[84:87], v[210:213]
	v_mfma_f32_16x16x32_bf16 v[214:217], v[32:35], v[100:103], v[214:217]
	v_mfma_f32_16x16x32_bf16 v[218:221], v[36:39], v[100:103], v[218:221]
	v_mfma_f32_16x16x32_bf16 v[228:231], v[40:43], v[100:103], v[228:231]
	v_mfma_f32_16x16x32_bf16 v[232:235], v[44:47], v[100:103], v[232:235]
	ds_read_b128 v[32:35], v153 offset:192
	ds_read_b128 v[36:39], v153 offset:4544
	ds_read_b128 v[40:43], v153 offset:8928
	ds_read_b128 v[44:47], v153 offset:13280
	s_waitcnt lgkmcnt(4)
; __device__ __forceinline__ unsigned cvt_pk_bf16(float lo, float hi) { unsigned r; asm("v_cvt_pk_bf16_f32 %0, %1, %2" : "=v"(r) : "v"(lo), "v"(hi)); return r; }
; __device__ __forceinline__ float bf_lo(unsigned w) { return __uint_as_float(w << 16); }
; __device__ __forceinline__ float bf_hi(unsigned w) { return __uint_as_float(w & 0xffff0000u); }
; __device__ __forceinline__ void gmlp_task(LAS unsigned char* lds, const bf16_t* zina, const bf16_t* wsb, const float* vg, const float* bs, bf16_t* y, int task) {
;     ...
; #pragma unroll
;         for (int mq = 0; mq < 2; ++mq)
; #pragma unroll
;             for (int nd = 0; nd < 4; ++nd) acc[mq][nd] = __builtin_amdgcn_mfma_f32_16x16x32_bf16(bfr[nd], af[mq], acc[mq][nd], 0, 0, 0);
;     }
;     u32x2 uq[2][4];
; #pragma unroll
;     for (int mq = 0; mq < 2; ++mq)
; #pragma unroll
;         for (int nd = 0; nd < 4; ++nd) uq[mq][nd] = *(const u32x2*)(zina + (size_t)(t0 + q0 + mq * 16 + fr) * 1536 + h * 128 + d0 + nd * 16 + 4 * fq);
; #pragma unroll
;     for (int mq = 0; mq < 2; ++mq) { const int q = q0 + mq * 16 + fr; const float b = bs[h * 128 + q];
; #pragma unroll
;         for (int nd = 0; nd < 4; ++nd) { const int d = d0 + nd * 16 + 4 * fq;
;             const u32x2 uu = uq[mq][nd];
;             const f32x4 m = acc[mq][nd] + b;
;             u32x2 o; o.x = cvt_pk_bf16(bf_lo(uu.x) * m[0], bf_hi(uu.x) * m[1]); o.y = cvt_pk_bf16(bf_lo(uu.y) * m[2], bf_hi(uu.y) * m[3]);
;             *(u32x2*)(y + (size_t)(t0 + q) * 2048 + h * 128 + d) = o; } }
;     __syncthreads();
	v_mfma_f32_16x16x32_bf16 v[198:201], v[16:19], v[88:91], v[198:201]
	v_mfma_f32_16x16x32_bf16 v[202:205], v[20:23], v[88:91], v[202:205]
	v_mfma_f32_16x16x32_bf16 v[206:209], v[24:27], v[88:91], v[206:209]
	v_mfma_f32_16x16x32_bf16 v[210:213], v[28:31], v[88:91], v[210:213]
	v_mfma_f32_16x16x32_bf16 v[214:217], v[16:19], v[104:107], v[214:217]
	v_mfma_f32_16x16x32_bf16 v[218:221], v[20:23], v[104:107], v[218:221]
	v_mfma_f32_16x16x32_bf16 v[228:231], v[24:27], v[104:107], v[228:231]
	v_mfma_f32_16x16x32_bf16 v[232:235], v[28:31], v[104:107], v[232:235]
	s_waitcnt lgkmcnt(0)
	v_mfma_f32_16x16x32_bf16 v[198:201], v[32:35], v[92:95], v[198:201]
	v_mfma_f32_16x16x32_bf16 v[202:205], v[36:39], v[92:95], v[202:205]
	v_mfma_f32_16x16x32_bf16 v[206:209], v[40:43], v[92:95], v[206:209]
	v_mfma_f32_16x16x32_bf16 v[210:213], v[44:47], v[92:95], v[210:213]
	v_mfma_f32_16x16x32_bf16 v[214:217], v[32:35], v[108:111], v[214:217]
	v_mfma_f32_16x16x32_bf16 v[218:221], v[36:39], v[108:111], v[218:221]
	v_mfma_f32_16x16x32_bf16 v[228:231], v[40:43], v[108:111], v[228:231]
	v_mfma_f32_16x16x32_bf16 v[232:235], v[44:47], v[108:111], v[232:235]
	s_lshl_b32 s28, s34, 19
	s_lshl_b32 s37, s35, 8
	s_add_i32 s28, s28, s37
	v_add_u32_e32 v166, s28, v157
	v_add_u32_e32 v167, s28, v158
	s_waitcnt vmcnt(4)
	s_nop 7
	v_add_f32_e32 v198, v198, v146
	v_add_f32_e32 v199, v199, v146
	v_add_f32_e32 v200, v200, v146
	v_add_f32_e32 v201, v201, v146
	v_lshlrev_b32_e32 v160, 16, v112
	v_and_b32_e32 v161, 0xffff0000, v112
	v_lshlrev_b32_e32 v162, 16, v113
	v_and_b32_e32 v163, 0xffff0000, v113
	v_mul_f32_e32 v198, v198, v160
	v_mul_f32_e32 v199, v199, v161
	v_mul_f32_e32 v200, v200, v162
	v_mul_f32_e32 v201, v201, v163
	v_cvt_pk_bf16_f32 v198, v198, v199
	v_cvt_pk_bf16_f32 v199, v200, v201
	global_store_dwordx2 v166, v[198:199], s[50:51]
	v_add_f32_e32 v202, v202, v146
	v_add_f32_e32 v203, v203, v146
	v_add_f32_e32 v204, v204, v146
	v_add_f32_e32 v205, v205, v146
	v_lshlrev_b32_e32 v160, 16, v114
	v_and_b32_e32 v161, 0xffff0000, v114
	v_lshlrev_b32_e32 v162, 16, v115
	v_and_b32_e32 v163, 0xffff0000, v115
	v_mul_f32_e32 v202, v202, v160
	v_mul_f32_e32 v203, v203, v161
	v_mul_f32_e32 v204, v204, v162
	v_mul_f32_e32 v205, v205, v163
	v_cvt_pk_bf16_f32 v202, v202, v203
	v_cvt_pk_bf16_f32 v203, v204, v205
	global_store_dwordx2 v166, v[202:203], s[50:51] offset:32
	v_add_f32_e32 v206, v206, v146
	v_add_f32_e32 v207, v207, v146
	v_add_f32_e32 v208, v208, v146
	v_add_f32_e32 v209, v209, v146
	v_lshlrev_b32_e32 v160, 16, v116
	v_and_b32_e32 v161, 0xffff0000, v116
	v_lshlrev_b32_e32 v162, 16, v117
	v_and_b32_e32 v163, 0xffff0000, v117
	v_mul_f32_e32 v206, v206, v160
	v_mul_f32_e32 v207, v207, v161
	v_mul_f32_e32 v208, v208, v162
	v_mul_f32_e32 v209, v209, v163
	v_cvt_pk_bf16_f32 v206, v206, v207
	v_cvt_pk_bf16_f32 v207, v208, v209
	global_store_dwordx2 v166, v[206:207], s[50:51] offset:64
	v_add_f32_e32 v210, v210, v146
	v_add_f32_e32 v211, v211, v146
	v_add_f32_e32 v212, v212, v146
	v_add_f32_e32 v213, v213, v146
	v_lshlrev_b32_e32 v160, 16, v118
	v_and_b32_e32 v161, 0xffff0000, v118
	v_lshlrev_b32_e32 v162, 16, v119
	v_and_b32_e32 v163, 0xffff0000, v119
	v_mul_f32_e32 v210, v210, v160
	v_mul_f32_e32 v211, v211, v161
	v_mul_f32_e32 v212, v212, v162
	v_mul_f32_e32 v213, v213, v163
	v_cvt_pk_bf16_f32 v210, v210, v211
	v_cvt_pk_bf16_f32 v211, v212, v213
	global_store_dwordx2 v166, v[210:211], s[50:51] offset:96
	v_add_f32_e32 v214, v214, v147
	v_add_f32_e32 v215, v215, v147
	v_add_f32_e32 v216, v216, v147
	v_add_f32_e32 v217, v217, v147
	v_lshlrev_b32_e32 v160, 16, v120
	v_and_b32_e32 v161, 0xffff0000, v120
	v_lshlrev_b32_e32 v162, 16, v121
	v_and_b32_e32 v163, 0xffff0000, v121
	v_mul_f32_e32 v214, v214, v160
	v_mul_f32_e32 v215, v215, v161
	v_mul_f32_e32 v216, v216, v162
	v_mul_f32_e32 v217, v217, v163
	v_cvt_pk_bf16_f32 v214, v214, v215
	v_cvt_pk_bf16_f32 v215, v216, v217
	global_store_dwordx2 v167, v[214:215], s[50:51]
	v_add_f32_e32 v218, v218, v147
	v_add_f32_e32 v219, v219, v147
	v_add_f32_e32 v220, v220, v147
	v_add_f32_e32 v221, v221, v147
	v_lshlrev_b32_e32 v160, 16, v122
	v_and_b32_e32 v161, 0xffff0000, v122
	v_lshlrev_b32_e32 v162, 16, v123
	v_and_b32_e32 v163, 0xffff0000, v123
	v_mul_f32_e32 v218, v218, v160
	v_mul_f32_e32 v219, v219, v161
	v_mul_f32_e32 v220, v220, v162
	v_mul_f32_e32 v221, v221, v163
	v_cvt_pk_bf16_f32 v218, v218, v219
	v_cvt_pk_bf16_f32 v219, v220, v221
	global_store_dwordx2 v167, v[218:219], s[50:51] offset:32
	v_add_f32_e32 v228, v228, v147
	v_add_f32_e32 v229, v229, v147
	v_add_f32_e32 v230, v230, v147
	v_add_f32_e32 v231, v231, v147
	v_lshlrev_b32_e32 v160, 16, v124
	v_and_b32_e32 v161, 0xffff0000, v124
	v_lshlrev_b32_e32 v162, 16, v125
	v_and_b32_e32 v163, 0xffff0000, v125
	v_mul_f32_e32 v228, v228, v160
	v_mul_f32_e32 v229, v229, v161
	v_mul_f32_e32 v230, v230, v162
	v_mul_f32_e32 v231, v231, v163
	v_cvt_pk_bf16_f32 v228, v228, v229
	v_cvt_pk_bf16_f32 v229, v230, v231
	global_store_dwordx2 v167, v[228:229], s[50:51] offset:64
	v_add_f32_e32 v232, v232, v147
	v_add_f32_e32 v233, v233, v147
	v_add_f32_e32 v234, v234, v147
	v_add_f32_e32 v235, v235, v147
	v_lshlrev_b32_e32 v160, 16, v126
	v_and_b32_e32 v161, 0xffff0000, v126
	v_lshlrev_b32_e32 v162, 16, v127
	v_and_b32_e32 v163, 0xffff0000, v127
	v_mul_f32_e32 v232, v232, v160
	v_mul_f32_e32 v233, v233, v161
	v_mul_f32_e32 v234, v234, v162
	v_mul_f32_e32 v235, v235, v163
	v_cvt_pk_bf16_f32 v232, v232, v233
	v_cvt_pk_bf16_f32 v233, v234, v235
	global_store_dwordx2 v167, v[232:233], s[50:51] offset:96
	s_barrier
	s_add_i32 s0, s0, s2
	s_cmp_lt_i32 s0, s33
	s_cbranch_scc1 .Lgm_task
	s_waitcnt vmcnt(0)
